# B-unit tile loop: V fragment reads of the second-half PV hoisted above the preceding MFMAs into dead fragment registers, lgkmcnt recounted
# baseline (speedup 1.0000x reference)
; #define LAS __attribute__((address_space(3)))
; #define LAS __attribute__((address_space(3)))
; __device__ __forceinline__ void unit_b(const AttnArgs& A, int b, int h, int qb, LAS unsigned char* lds) {
;     ...
;             const LAS unsigned char* kimg = lds + st * 32768 + mp * 8192; const LAS unsigned char* vimg = lds + st * 32768 + 16384;
;             qkt_half(p0, kimg, qr, r32, hi, -M0, 0); qkt_half(p1, kimg, qr, r32, hi, -M0, 1);
;             const float dq = (float)(qrow - 64 * t - 4 * hi);
;             float sum0 = 0.f, sum1 = 0.f;
; #pragma unroll
;             for (int r = 0; r < 16; ++r) { const float kk = (float)((r & 3) + 8 * (r >> 2)); p0[r] = __builtin_amdgcn_exp2f(p0[r] - slope2 * fabsf(dq - kk)); sum0 += p0[r]; }
;             pv_half<4>(o, vimg, vl, p0, 0);
; #pragma unroll
;             for (int r = 0; r < 16; ++r) { const float kk = (float)((r & 3) + 8 * (r >> 2)); p1[r] = __builtin_amdgcn_exp2f(p1[r] - slope2 * fabsf(dq - kk - 32.0f)); sum1 += p1[r]; }
;             pv_half<4>(o, vimg, vl, p1, 1);
.LBB0_441:
	s_lshl_b32 s0, s13, 15
	s_add_i32 s0, s0, 0
	s_add_i32 s1, s0, s26
	v_add3_u32 v162, s1, v193, v251
	ds_read_b128 v[82:85], v162
	ds_read_b128 v[86:89], v162 offset:2048
	ds_read_b128 v[90:93], v162 offset:4096
	ds_read_b128 v[94:97], v162 offset:6144
	ds_read_b128 v[150:153], v162 offset:512
	ds_read_b128 v[154:157], v162 offset:2560
	ds_read_b128 v[158:161], v162 offset:4608
	ds_read_b128 v[162:165], v162 offset:6656
	s_waitcnt lgkmcnt(7)
	v_mfma_f32_32x32x16_bf16 v[98:113], v[82:85], v[146:149], v[66:81]
	v_cvt_f32_i32_e32 v203, v252
	v_add_f32_e32 v205, -1.0, v203
	v_add_f32_e32 v207, -2.0, v203
	v_add_f32_e32 v209, 0xc0400000, v203
	s_waitcnt lgkmcnt(6)
	v_mfma_f32_32x32x16_bf16 v[98:113], v[86:89], v[142:145], v[98:113]
	v_add_f32_e32 v211, 0xc1000000, v203
	v_add_f32_e32 v213, 0xc1100000, v203
	v_add_f32_e32 v215, 0xc1200000, v203
	v_add_f32_e32 v217, 0xc1300000, v203
	v_add_f32_e32 v219, 0xc1800000, v203
	v_add_f32_e32 v221, 0xc1880000, v203
	v_add_f32_e32 v223, 0xc1900000, v203
	s_waitcnt lgkmcnt(5)
	v_mfma_f32_32x32x16_bf16 v[98:113], v[90:93], v[138:141], v[98:113]
	v_add_f32_e32 v225, 0xc1980000, v203
	v_add_f32_e32 v227, 0xc1c00000, v203
	v_add_f32_e32 v229, 0xc1c80000, v203
	v_add_f32_e32 v231, 0xc1d00000, v203
	v_add_f32_e32 v233, 0xc1d80000, v203
	s_waitcnt lgkmcnt(4)
	v_mfma_f32_32x32x16_bf16 v[98:113], v[94:97], v[134:137], v[98:113]
	s_waitcnt lgkmcnt(3)
	v_mfma_f32_32x32x16_bf16 v[82:97], v[150:153], v[146:149], v[66:81]
	s_nop 9
	v_fma_f32 v98, -v182, |v203|, v98
	v_add_f32_e32 v203, 0xc2000000, v203
	v_exp_f32_e32 v202, v98
	v_fma_f32 v98, -v182, |v205|, v99
	v_exp_f32_e32 v204, v98
	v_fma_f32 v98, -v182, |v207|, v100
	v_exp_f32_e32 v206, v98
	s_waitcnt lgkmcnt(2)
	v_mfma_f32_32x32x16_bf16 v[82:97], v[154:157], v[142:145], v[82:97]
	v_fma_f32 v98, -v182, |v209|, v101
	v_exp_f32_e32 v208, v98
	v_fma_f32 v98, -v182, |v211|, v102
	v_exp_f32_e32 v210, v98
	v_fma_f32 v98, -v182, |v213|, v103
	v_exp_f32_e32 v212, v98
	v_fma_f32 v98, -v182, |v215|, v104
	s_waitcnt lgkmcnt(1)
	v_mfma_f32_32x32x16_bf16 v[82:97], v[158:161], v[138:141], v[82:97]
	v_exp_f32_e32 v214, v98
	v_fma_f32 v98, -v182, |v217|, v105
	v_exp_f32_e32 v216, v98
	v_fma_f32 v98, -v182, |v219|, v106
	v_exp_f32_e32 v218, v98
	v_fma_f32 v98, -v182, |v221|, v107
	v_exp_f32_e32 v220, v98
	s_waitcnt lgkmcnt(0)
	v_mfma_f32_32x32x16_bf16 v[82:97], v[162:165], v[134:137], v[82:97]
	v_fma_f32 v98, -v182, |v223|, v108
	v_exp_f32_e32 v222, v98
	v_fma_f32 v98, -v182, |v225|, v109
	v_exp_f32_e32 v224, v98
	v_fma_f32 v98, -v182, |v227|, v110
	v_exp_f32_e32 v226, v98
	v_fma_f32 v98, -v182, |v229|, v111
	s_nop 4
	v_fma_f32 v82, -v182, |v203|, v82
	v_exp_f32_e32 v203, v82
	v_add_f32_e32 v82, 0xc2000000, v205
	v_fma_f32 v82, -v182, |v82|, v83
	v_exp_f32_e32 v205, v82
	v_add_f32_e32 v82, 0xc2000000, v207
	v_fma_f32 v82, -v182, |v82|, v84
	v_exp_f32_e32 v207, v82
	v_add_f32_e32 v82, 0xc2000000, v209
	v_fma_f32 v82, -v182, |v82|, v85
	v_exp_f32_e32 v209, v82
	v_add_f32_e32 v82, 0xc2000000, v211
	v_fma_f32 v82, -v182, |v82|, v86
	v_exp_f32_e32 v211, v82
	v_add_f32_e32 v82, 0xc2000000, v213
	v_fma_f32 v82, -v182, |v82|, v87
	v_exp_f32_e32 v213, v82
	v_add_f32_e32 v82, 0xc2000000, v215
	v_fma_f32 v82, -v182, |v82|, v88
	v_exp_f32_e32 v215, v82
	v_add_f32_e32 v82, 0xc2000000, v217
	v_fma_f32 v82, -v182, |v82|, v89
	v_exp_f32_e32 v217, v82
	v_add_f32_e32 v82, 0xc2000000, v219
	v_fma_f32 v82, -v182, |v82|, v90
	v_exp_f32_e32 v219, v82
	v_add_f32_e32 v82, 0xc2000000, v221
	v_fma_f32 v82, -v182, |v82|, v91
	v_exp_f32_e32 v221, v82
	v_add_f32_e32 v82, 0xc2000000, v223
	v_fma_f32 v82, -v182, |v82|, v92
	v_exp_f32_e32 v223, v82
	v_add_f32_e32 v82, 0xc2000000, v225
	v_fma_f32 v82, -v182, |v82|, v93
	v_exp_f32_e32 v225, v82
	v_add_f32_e32 v82, 0xc2000000, v227
	v_fma_f32 v82, -v182, |v82|, v94
	v_exp_f32_e32 v227, v82
	v_add_f32_e32 v82, 0xc2000000, v229
	v_fma_f32 v82, -v182, |v82|, v95
	v_exp_f32_e32 v229, v82
	v_add_f32_e32 v82, 0xc2000000, v231
	v_exp_f32_e32 v228, v98
	v_fma_f32 v98, -v182, |v231|, v112
	v_fma_f32 v82, -v182, |v82|, v96
	v_pk_add_f32 v[84:85], v[202:203], 0 op_sel_hi:[1,0]
	v_exp_f32_e32 v230, v98
	v_fma_f32 v98, -v182, |v233|, v113
	v_exp_f32_e32 v231, v82
	v_add_f32_e32 v82, 0xc2000000, v233
	v_pk_add_f32 v[84:85], v[204:205], v[84:85]
	v_exp_f32_e32 v232, v98
	v_add_u32_e32 v98, s0, v248
	v_fma_f32 v82, -v182, |v82|, v97
	v_pk_add_f32 v[84:85], v[206:207], v[84:85]
	v_add3_u32 v253, v98, v249, v247
	v_exp_f32_e32 v233, v82
	v_cvt_pk_bf16_f32 v82, v202, v204
	v_cvt_pk_bf16_f32 v83, v206, v208
	v_pk_add_f32 v[90:91], v[208:209], v[84:85]
	v_cvt_pk_bf16_f32 v84, v210, v212
	v_cvt_pk_bf16_f32 v85, v214, v216
	ds_read_b64_tr_b16 v[162:163], v253 offset:16384
	ds_read_b64_tr_b16 v[164:165], v253 offset:16896
	ds_read_b64_tr_b16 v[158:159], v253 offset:17408
	ds_read_b64_tr_b16 v[160:161], v253 offset:17920
	ds_read_b64_tr_b16 v[154:155], v253 offset:20480
	ds_read_b64_tr_b16 v[156:157], v253 offset:20992
	ds_read_b64_tr_b16 v[150:151], v253 offset:21504
	ds_read_b64_tr_b16 v[152:153], v253 offset:22016
	ds_read_b64_tr_b16 v[110:111], v253 offset:24576
	ds_read_b64_tr_b16 v[112:113], v253 offset:25088
	ds_read_b64_tr_b16 v[106:107], v253 offset:25600
	ds_read_b64_tr_b16 v[108:109], v253 offset:26112
	ds_read_b64_tr_b16 v[98:99], v253 offset:28672
	ds_read_b64_tr_b16 v[100:101], v253 offset:29184
	ds_read_b64_tr_b16 v[102:103], v253 offset:29696
	ds_read_b64_tr_b16 v[104:105], v253 offset:30208
	s_waitcnt lgkmcnt(14)
; __device__ __forceinline__ void unit_b(const AttnArgs& A, int b, int h, int qb, LAS unsigned char* lds) {
;     ...
;             pv_half<4>(o, vimg, vl, p0, 0);
; #pragma unroll
;             for (int r = 0; r < 16; ++r) { const float kk = (float)((r & 3) + 8 * (r >> 2)); p1[r] = __builtin_amdgcn_exp2f(p1[r] - slope2 * fabsf(dq - kk - 32.0f)); sum1 += p1[r]; }
;             pv_half<4>(o, vimg, vl, p1, 1);
;             l_run += sum0 + sum1;
	v_mfma_f32_32x32x16_bf16 v[2:17], v[162:165], v[82:85], v[2:17]
	v_cvt_pk_bf16_f32 v86, v218, v220
	v_cvt_pk_bf16_f32 v87, v222, v224
	v_cvt_pk_bf16_f32 v88, v226, v228
	v_cvt_pk_bf16_f32 v89, v230, v232
	s_waitcnt lgkmcnt(10)
	v_mfma_f32_32x32x16_bf16 v[18:33], v[154:157], v[82:85], v[18:33]
	s_waitcnt lgkmcnt(6)
	v_mfma_f32_32x32x16_bf16 v[34:49], v[110:113], v[82:85], v[34:49]
	s_waitcnt lgkmcnt(2)
	v_mfma_f32_32x32x16_bf16 v[50:65], v[98:101], v[82:85], v[50:65]
	v_add_f32_e64 v82, v210, v90
	v_add_f32_e64 v83, v211, v91
	ds_read_b64_tr_b16 v[92:93], v253 offset:18432
	ds_read_b64_tr_b16 v[94:95], v253 offset:18944
	ds_read_b64_tr_b16 v[96:97], v253 offset:19456
	ds_read_b64_tr_b16 v[98:99], v253 offset:19968
	ds_read_b64_tr_b16 v[162:163], v253 offset:22528
	ds_read_b64_tr_b16 v[164:165], v253 offset:23040
	ds_read_b64_tr_b16 v[154:155], v253 offset:23552
	ds_read_b64_tr_b16 v[156:157], v253 offset:24064
	v_pk_add_f32 v[82:83], v[212:213], v[82:83]
	v_cvt_pk_bf16_f32 v84, v227, v229
	v_pk_add_f32 v[82:83], v[214:215], v[82:83]
	v_cvt_pk_bf16_f32 v85, v231, v233
	v_pk_add_f32 v[82:83], v[216:217], v[82:83]
	v_mfma_f32_32x32x16_bf16 v[2:17], v[158:161], v[86:89], v[2:17]
	v_add_f32_e64 v82, v218, v82
	v_add_f32_e64 v83, v219, v83
	ds_read_b64_tr_b16 v[110:111], v253 offset:26624
	ds_read_b64_tr_b16 v[112:113], v253 offset:27136
	ds_read_b64_tr_b16 v[158:159], v253 offset:27648
	ds_read_b64_tr_b16 v[160:161], v253 offset:28160
	v_add_f32_e64 v82, v220, v82
	v_add_f32_e64 v83, v221, v83
	v_add_f32_e64 v82, v222, v82
	v_add_f32_e64 v83, v223, v83
	v_pk_add_f32 v[82:83], v[224:225], v[82:83]
	v_mfma_f32_32x32x16_bf16 v[18:33], v[150:153], v[86:89], v[18:33]
	v_add_f32_e64 v82, v226, v82
	v_add_f32_e64 v83, v227, v83
	v_add_f32_e64 v82, v228, v82
	v_add_f32_e64 v83, v229, v83
	v_add_f32_e64 v82, v230, v82
	v_add_f32_e64 v83, v231, v83
	v_pk_add_f32 v[90:91], v[232:233], v[82:83]
	v_mfma_f32_32x32x16_bf16 v[34:49], v[106:109], v[86:89], v[34:49]
	v_cvt_pk_bf16_f32 v82, v219, v221
	v_cvt_pk_bf16_f32 v83, v223, v225
	s_waitcnt lgkmcnt(12)
	v_mfma_f32_32x32x16_bf16 v[50:65], v[102:105], v[86:89], v[50:65]
	ds_read_b64_tr_b16 v[150:151], v253 offset:30720
	ds_read_b64_tr_b16 v[152:153], v253 offset:31232
	ds_read_b64_tr_b16 v[106:107], v253 offset:31744
	ds_read_b64_tr_b16 v[108:109], v253 offset:32256
	v_cvt_pk_bf16_f32 v86, v203, v205
	v_cvt_pk_bf16_f32 v87, v207, v209
	v_cvt_pk_bf16_f32 v88, v211, v213
	v_cvt_pk_bf16_f32 v89, v215, v217
	s_waitcnt lgkmcnt(14)
	s_nop 0
	v_mfma_f32_32x32x16_bf16 v[2:17], v[92:95], v[86:89], v[2:17]
	s_waitcnt lgkmcnt(12)
	v_mfma_f32_32x32x16_bf16 v[2:17], v[96:99], v[82:85], v[2:17]
	s_waitcnt lgkmcnt(10)
	v_mfma_f32_32x32x16_bf16 v[18:33], v[162:165], v[86:89], v[18:33]
	s_waitcnt lgkmcnt(8)
	v_mfma_f32_32x32x16_bf16 v[18:33], v[154:157], v[82:85], v[18:33]
	s_waitcnt lgkmcnt(6)
	v_mfma_f32_32x32x16_bf16 v[34:49], v[110:113], v[86:89], v[34:49]
	s_waitcnt lgkmcnt(4)
	v_mfma_f32_32x32x16_bf16 v[34:49], v[158:161], v[82:85], v[34:49]
	s_waitcnt lgkmcnt(2)
	v_mfma_f32_32x32x16_bf16 v[50:65], v[150:153], v[86:89], v[50:65]
	s_waitcnt lgkmcnt(0)
	v_mfma_f32_32x32x16_bf16 v[50:65], v[106:109], v[82:85], v[50:65]
	v_add_f32_e32 v82, v90, v91
	v_add_f32_e32 v0, v0, v82
	s_andn2_b64 vcc, exec, s[8:9]
	s_cbranch_vccz .LBB0_437
	s_branch .LBB0_438
